# start-up grid sync: every wave drains its write-through zeroing stores before arriving, and the L2 write-back there (nothing of this kernel to publish yet) is dropped
# baseline (speedup 1.0000x reference)
.LBB0_6:
	v_lshrrev_b32_e32 v1, 20, v0
	v_lshrrev_b32_e32 v0, 10, v0
	v_or_b32_e32 v0, v0, v1
	s_movk_i32 s2, 0x3ff
	v_and_or_b32 v0, v0, s2, v224
	v_cmp_eq_u32_e32 vcc, 0, v0
	s_waitcnt vmcnt(0) lgkmcnt(0)
	s_barrier
	s_and_saveexec_b64 s[2:3], vcc
	s_cbranch_execz .LBB0_16
	v_readlane_b32 s4, v253, 1
	v_readlane_b32 s5, v253, 2
	s_waitcnt vmcnt(0)
	s_load_dwordx2 s[4:5], s[4:5], 0x58
	v_mov_b32_e32 v2, 0
	s_mov_b64 s[6:7], exec
	v_mbcnt_lo_u32_b32 v1, s6, 0
	v_mbcnt_hi_u32_b32 v1, s7, v1
	s_waitcnt lgkmcnt(0)
	global_load_dword v0, v2, s[4:5] offset:40
	v_cmp_eq_u32_e32 vcc, 0, v1
	s_and_saveexec_b64 s[8:9], vcc
	s_cbranch_execz .LBB0_9
	s_bcnt1_i32_b64 s6, s[6:7]
	v_mov_b32_e32 v3, s6
	global_atomic_add v3, v2, v3, s[4:5] offset:32 sc0
